# attention loop: the six LDS-DMA issues moved from the loop head into the softmax groups of tile A (VALU-dominated gaps)
# speedup vs baseline: 1.0061x; 1.0058x over previous
; #define AT_LOAD(X, t) do { const size_t adv_ = (size_t)(t) * 64; sk##X = *(const u32x4*)(gk + adv_ * 1024); sv##X = *(const u32x4*)(gv + adv_ * 1024); if (rth) sr##X = *(const u32x4*)(gr + adv_ * 32); } while (0)
; #define AT_STORE(X, slot) do { *(LAS u32x4*)(lds + A_K0 + (slot) * AK_BYTES + lk) = sk##X; *(LAS u32x4*)(lds + A_V0 + (slot) * AV_BYTES + lv) = sv##X; if (rth) *(LAS u32x4*)(lds + A_K0 + (slot) * AK_BYTES + lr) = sr##X; } while (0)
; __device__ __forceinline__ void attn_unit(LAS char* lds, const bf16_t* Qp, const bf16_t* KVp, const bf16_t* KRp, int ntiles, bf16_t* Yp, bool dry) {
;     ...
;     for (int t = 0; t < ntiles; t += 2) {
;         const int sb0 = (t & 2);
;         const bool more = (t + 2 < ntiles);
;         f32x16 pa0 = {}, pa1 = {}, pb0 = {}, pb1 = {};
;         AT_QK(sb0, pa0, pa1);
;         AT_QK(sb0 + 1, pb0, pb1);
;         if (t == 0) AT_SMPV(sb0, true, pa0, pa1); else AT_SMPV(sb0, false, pa0, pa1);
;         __builtin_amdgcn_sched_barrier(0);
;         if (more) { AT_LOAD(A, t + 2); AT_LOAD(B, t + 3); }
;         AT_SMPV(sb0 + 1, false, pb0, pb1);
;         if (more) { AT_STORE(A, sb0 ^ 2); AT_STORE(B, (sb0 ^ 2) + 1); }
.Latt_loop:
	s_and_b32 s42, s35, 2
	s_mul_i32 s2, s42, 0x3400
	v_add_u32_e32 v0, s2, v209
	v_lshl_add_u32 v185, s42, 13, v208
	v_add_u32_e32 v184, 0x2000, v185
	ds_read_b128 v[66:69], v0 offset:0
	ds_read_b128 v[70:73], v0 offset:6656
	ds_read_b128 v[74:77], v0 offset:32
	ds_read_b128 v[78:81], v0 offset:6688
	ds_read_b128 v[212:215], v0 offset:64
	ds_read_b128 v[240:243], v0 offset:6720
	ds_read_b128 v[244:247], v0 offset:96
	s_waitcnt lgkmcnt(6)
	v_mfma_f32_32x32x16_bf16 v[114:129], v[66:69], v[154:157], v[82:97]
	ds_read_b128 v[248:251], v0 offset:6752
	s_waitcnt lgkmcnt(6)
	v_mfma_f32_32x32x16_bf16 v[98:113], v[70:73], v[154:157], v[82:97]
	ds_read_b128 v[66:69], v0 offset:128
	s_waitcnt lgkmcnt(6)
	v_mfma_f32_32x32x16_bf16 v[114:129], v[74:77], v[158:161], v[114:129]
	ds_read_b128 v[70:73], v0 offset:6784
	s_waitcnt lgkmcnt(6)
	v_mfma_f32_32x32x16_bf16 v[98:113], v[78:81], v[158:161], v[98:113]
	ds_read_b128 v[74:77], v0 offset:160
	s_waitcnt lgkmcnt(6)
	v_mfma_f32_32x32x16_bf16 v[114:129], v[212:215], v[162:165], v[114:129]
	ds_read_b128 v[78:81], v0 offset:6816
	s_waitcnt lgkmcnt(6)
	v_mfma_f32_32x32x16_bf16 v[98:113], v[240:243], v[162:165], v[98:113]
	ds_read_b128 v[212:215], v0 offset:13312
	s_waitcnt lgkmcnt(6)
	v_mfma_f32_32x32x16_bf16 v[114:129], v[244:247], v[166:169], v[114:129]
	ds_read_b128 v[240:243], v0 offset:19968
	s_waitcnt lgkmcnt(6)
	v_mfma_f32_32x32x16_bf16 v[98:113], v[248:251], v[166:169], v[98:113]
	ds_read_b128 v[244:247], v0 offset:13344
	s_waitcnt lgkmcnt(6)
	v_mfma_f32_32x32x16_bf16 v[114:129], v[66:69], v[170:173], v[114:129]
	ds_read_b128 v[248:251], v0 offset:20000
	s_waitcnt lgkmcnt(6)
	v_mfma_f32_32x32x16_bf16 v[98:113], v[70:73], v[170:173], v[98:113]
	ds_read_b128 v[66:69], v0 offset:13376
	s_waitcnt lgkmcnt(6)
	v_mfma_f32_32x32x16_bf16 v[114:129], v[74:77], v[174:177], v[114:129]
	ds_read_b128 v[70:73], v0 offset:20032
	s_waitcnt lgkmcnt(6)
	v_mfma_f32_32x32x16_bf16 v[98:113], v[78:81], v[174:177], v[98:113]
	ds_read_b128 v[74:77], v0 offset:13408
	s_waitcnt lgkmcnt(6)
	v_mfma_f32_32x32x16_bf16 v[2:17], v[212:215], v[154:157], v[82:97]
	ds_read_b128 v[78:81], v0 offset:20064
	s_waitcnt lgkmcnt(6)
	v_mfma_f32_32x32x16_bf16 v[18:33], v[240:243], v[154:157], v[82:97]
	ds_read_b128 v[212:215], v0 offset:13440
	s_waitcnt lgkmcnt(6)
	v_mfma_f32_32x32x16_bf16 v[2:17], v[244:247], v[158:161], v[2:17]
	ds_read_b128 v[240:243], v0 offset:20096
	s_waitcnt lgkmcnt(6)
	v_mfma_f32_32x32x16_bf16 v[18:33], v[248:251], v[158:161], v[18:33]
	ds_read_b128 v[244:247], v0 offset:13472
	s_waitcnt lgkmcnt(6)
	v_mfma_f32_32x32x16_bf16 v[2:17], v[66:69], v[162:165], v[2:17]
	ds_read_b128 v[248:251], v0 offset:20128
	s_waitcnt lgkmcnt(6)
	v_mfma_f32_32x32x16_bf16 v[18:33], v[70:73], v[162:165], v[18:33]
	ds_read_b64_tr_b16 v[216:217], v185 offset:53248
	ds_read_b64_tr_b16 v[218:219], v185 offset:53760
	s_waitcnt lgkmcnt(7)
	v_mfma_f32_32x32x16_bf16 v[2:17], v[74:77], v[166:169], v[2:17]
	ds_read_b64_tr_b16 v[220:221], v185 offset:57344
	ds_read_b64_tr_b16 v[222:223], v185 offset:57856
	s_waitcnt lgkmcnt(8)
	v_mfma_f32_32x32x16_bf16 v[18:33], v[78:81], v[166:169], v[18:33]
	ds_read_b64_tr_b16 v[224:225], v185 offset:54272
	ds_read_b64_tr_b16 v[226:227], v185 offset:54784
	s_waitcnt lgkmcnt(9)
	v_mfma_f32_32x32x16_bf16 v[2:17], v[212:215], v[170:173], v[2:17]
	ds_read_b64_tr_b16 v[228:229], v185 offset:58368
	ds_read_b64_tr_b16 v[230:231], v185 offset:58880
	s_waitcnt lgkmcnt(10)
	v_mfma_f32_32x32x16_bf16 v[18:33], v[240:243], v[170:173], v[18:33]
	ds_read_b64_tr_b16 v[232:233], v185 offset:55296
	ds_read_b64_tr_b16 v[234:235], v185 offset:55808
	s_waitcnt lgkmcnt(11)
	v_mfma_f32_32x32x16_bf16 v[2:17], v[244:247], v[174:177], v[2:17]
	ds_read_b64_tr_b16 v[236:237], v185 offset:59392
	ds_read_b64_tr_b16 v[238:239], v185 offset:59904
	s_waitcnt lgkmcnt(12)
	v_mfma_f32_32x32x16_bf16 v[18:33], v[248:251], v[174:177], v[18:33]
	s_cmp_lg_u32 s35, 34
	s_cbranch_scc1 .Latt_nogate
	s_mul_i32 s14, s28, 0x1c00
	s_mul_hi_u32 s15, s25, 0x1c00
	s_add_i32 s15, s15, s14
	s_mul_i32 s14, s25, 0x1c00
	s_add_u32 s14, s88, s14
	s_addc_u32 s15, s89, s15
	s_lshl_b32 s2, s34, 1
	s_add_u32 s14, s14, s2
	s_addc_u32 s15, s15, 0
	v_lshlrev_b32_e32 v146, 1, v196
	v_mov_b32_e32 v147, 0
	s_mov_b64 s[2:3], 0x1000
	v_lshl_add_u64 v[146:147], s[14:15], 0, v[146:147]
	v_lshrrev_b32_e32 v148, 3, v191
	v_lshl_add_u64 v[146:147], v[146:147], 0, s[2:3]
	v_or_b32_e32 v148, s24, v148
	v_mad_i64_i32 v[150:151], s[16:17], v148, s13, v[146:147]
	v_or_b32_e32 v149, 8, v148
	global_load_dwordx4 v[130:133], v[150:151], off
	v_mad_i64_i32 v[152:153], s[16:17], v149, s13, v[146:147]
	v_or_b32_e32 v149, 16, v148
	global_load_dwordx4 v[134:137], v[152:153], off
	v_mad_i64_i32 v[150:151], s[16:17], v149, s13, v[146:147]
	v_or_b32_e32 v149, 24, v148
	global_load_dwordx4 v[138:141], v[150:151], off
	v_mad_i64_i32 v[152:153], s[16:17], v149, s13, v[146:147]
	s_nop 0
	global_load_dwordx4 v[142:145], v[152:153], off
.Latt_nogate:
	v_exp_f32_e32 v114, v114
	v_exp_f32_e32 v115, v115
	v_exp_f32_e32 v116, v116
	v_exp_f32_e32 v117, v117
	v_exp_f32_e32 v118, v118
	v_exp_f32_e32 v119, v119
	v_exp_f32_e32 v120, v120
	v_exp_f32_e32 v121, v121
	v_cvt_pk_bf16_f32 v66, v114, v115
	v_cvt_pk_bf16_f32 v67, v116, v117
	v_cvt_pk_bf16_f32 v68, v118, v119
	v_cvt_pk_bf16_f32 v69, v120, v121
	v_add_f32_e32 v178, v114, v115
	v_add_f32_e32 v179, v116, v117
	v_add_f32_e32 v180, v118, v119
	v_add_f32_e32 v181, v120, v121
	v_add_f32_e32 v178, v178, v179
	v_add_f32_e32 v180, v180, v181
	v_add_f32_e32 v178, v178, v180
	v_add_f32_e32 v210, v210, v178
	s_cmp_gt_u32 s35, 33
	s_cbranch_scc1 .Latt_nd0
	s_xor_b32 s14, s42, 2
	s_mul_i32 s15, s14, 0x3400
	s_lshl_b32 s16, s29, 10
	s_add_i32 s15, s15, s16
	s_mov_b32 m0, s15
	s_add_i32 s15, s15, 0x2000
	global_load_lds_dwordx4 v[130:131], off
	s_mov_b32 m0, s15
	s_add_i32 s15, s15, 0x2000
	global_load_lds_dwordx4 v[132:133], off
; #define AT_LOAD(X, t) do { const size_t adv_ = (size_t)(t) * 64; sk##X = *(const u32x4*)(gk + adv_ * 1024); sv##X = *(const u32x4*)(gv + adv_ * 1024); if (rth) sr##X = *(const u32x4*)(gr + adv_ * 32); } while (0)
; #define AT_STORE(X, slot) do { *(LAS u32x4*)(lds + A_K0 + (slot) * AK_BYTES + lk) = sk##X; *(LAS u32x4*)(lds + A_V0 + (slot) * AV_BYTES + lv) = sv##X; if (rth) *(LAS u32x4*)(lds + A_K0 + (slot) * AK_BYTES + lr) = sr##X; } while (0)
; __device__ __forceinline__ void attn_unit(LAS char* lds, const bf16_t* Qp, const bf16_t* KVp, const bf16_t* KRp, int ntiles, bf16_t* Yp, bool dry) {
;     ...
;     for (int t = 0; t < ntiles; t += 2) {
;         const int sb0 = (t & 2);
;         const bool more = (t + 2 < ntiles);
;         f32x16 pa0 = {}, pa1 = {}, pb0 = {}, pb1 = {};
;         AT_QK(sb0, pa0, pa1);
;         AT_QK(sb0 + 1, pb0, pb1);
;         if (t == 0) AT_SMPV(sb0, true, pa0, pa1); else AT_SMPV(sb0, false, pa0, pa1);
;         __builtin_amdgcn_sched_barrier(0);
;         if (more) { AT_LOAD(A, t + 2); AT_LOAD(B, t + 3); }
;         AT_SMPV(sb0 + 1, false, pb0, pb1);
;         if (more) { AT_STORE(A, sb0 ^ 2); AT_STORE(B, (sb0 ^ 2) + 1); }
.Latt_nd0:
	ds_read_b64_tr_b16 v[240:241], v185 offset:56320
	ds_read_b64_tr_b16 v[242:243], v185 offset:56832
	ds_read_b64_tr_b16 v[244:245], v185 offset:60416
	s_waitcnt lgkmcnt(11)
	ds_read_b64_tr_b16 v[246:247], v185 offset:60928
	ds_read_b64_tr_b16 v[114:115], v184 offset:53248
	ds_read_b64_tr_b16 v[116:117], v184 offset:53760
	ds_read_b64_tr_b16 v[118:119], v184 offset:57344
	s_waitcnt lgkmcnt(11)
	ds_read_b64_tr_b16 v[120:121], v184 offset:57856
	v_exp_f32_e32 v122, v122
	v_exp_f32_e32 v123, v123
	v_exp_f32_e32 v124, v124
	v_mfma_f32_32x32x16_bf16 v[34:49], v[66:69], v[216:219], v[34:49]
	v_exp_f32_e32 v125, v125
	v_exp_f32_e32 v126, v126
	v_exp_f32_e32 v127, v127
	v_exp_f32_e32 v128, v128
	v_exp_f32_e32 v129, v129
	v_cvt_pk_bf16_f32 v70, v122, v123
	v_cvt_pk_bf16_f32 v71, v124, v125
	v_mfma_f32_32x32x16_bf16 v[50:65], v[66:69], v[220:223], v[50:65]
	v_cvt_pk_bf16_f32 v72, v126, v127
	v_cvt_pk_bf16_f32 v73, v128, v129
	v_add_f32_e32 v178, v122, v123
	v_add_f32_e32 v179, v124, v125
	v_add_f32_e32 v180, v126, v127
	v_add_f32_e32 v181, v128, v129
	v_add_f32_e32 v178, v178, v179
	v_add_f32_e32 v180, v180, v181
	v_add_f32_e32 v178, v178, v180
	v_add_f32_e32 v210, v210, v178
	s_cmp_gt_u32 s35, 33
	s_cbranch_scc1 .Latt_nd1
	s_mov_b32 m0, s15
	s_add_i32 s15, s15, 0x2000
	global_load_lds_dwordx4 v[134:135], off
	s_cmp_gt_u32 s29, 1
	s_cbranch_scc1 .Latt_nd1
	s_mov_b32 m0, s15
	s_nop 0
	global_load_lds_dwordx4 v[136:137], off
.Latt_nd1:
	ds_read_b64_tr_b16 v[122:123], v184 offset:54272
	ds_read_b64_tr_b16 v[124:125], v184 offset:54784
	ds_read_b64_tr_b16 v[126:127], v184 offset:58368
	s_waitcnt lgkmcnt(11)
	ds_read_b64_tr_b16 v[128:129], v184 offset:58880
	v_exp_f32_e32 v98, v98
	v_exp_f32_e32 v99, v99
	v_exp_f32_e32 v100, v100
	v_mfma_f32_32x32x16_bf16 v[34:49], v[70:73], v[224:227], v[34:49]
	v_exp_f32_e32 v101, v101
	v_exp_f32_e32 v102, v102
	v_exp_f32_e32 v103, v103
	v_exp_f32_e32 v104, v104
	v_exp_f32_e32 v105, v105
	v_cvt_pk_bf16_f32 v74, v98, v99
	v_cvt_pk_bf16_f32 v75, v100, v101
	v_mfma_f32_32x32x16_bf16 v[50:65], v[70:73], v[228:231], v[50:65]
	v_cvt_pk_bf16_f32 v76, v102, v103
	v_cvt_pk_bf16_f32 v77, v104, v105
	v_add_f32_e32 v178, v98, v99
	v_add_f32_e32 v179, v100, v101
	v_add_f32_e32 v180, v102, v103
	v_add_f32_e32 v181, v104, v105
	v_add_f32_e32 v178, v178, v179
	v_add_f32_e32 v180, v180, v181
	v_add_f32_e32 v178, v178, v180
	v_add_f32_e32 v210, v210, v178
	s_cmp_gt_u32 s35, 33
	s_cbranch_scc1 .Latt_nd2
	s_lshl_b32 s15, s14, 13
	s_add_i32 s15, s15, s16
	s_add_i32 s15, s15, 0xd000
	s_mov_b32 m0, s15
	s_add_i32 s15, s15, 0x2000
	global_load_lds_dwordx4 v[138:139], off
	s_mov_b32 m0, s15
	s_nop 0
	global_load_lds_dwordx4 v[140:141], off
.Latt_nd2:
	ds_read_b64_tr_b16 v[98:99], v184 offset:55296
	ds_read_b64_tr_b16 v[100:101], v184 offset:55808
	ds_read_b64_tr_b16 v[102:103], v184 offset:59392
	s_waitcnt lgkmcnt(11)
	ds_read_b64_tr_b16 v[104:105], v184 offset:59904
	v_exp_f32_e32 v106, v106
	v_exp_f32_e32 v107, v107
	v_exp_f32_e32 v108, v108
	v_mfma_f32_32x32x16_bf16 v[34:49], v[74:77], v[232:235], v[34:49]
	v_exp_f32_e32 v109, v109
	v_exp_f32_e32 v110, v110
	v_exp_f32_e32 v111, v111
	v_exp_f32_e32 v112, v112
	v_exp_f32_e32 v113, v113
	v_cvt_pk_bf16_f32 v78, v106, v107
	v_cvt_pk_bf16_f32 v79, v108, v109
	v_mfma_f32_32x32x16_bf16 v[50:65], v[74:77], v[236:239], v[50:65]
	v_cvt_pk_bf16_f32 v80, v110, v111
	v_cvt_pk_bf16_f32 v81, v112, v113
	v_add_f32_e32 v178, v106, v107
	v_add_f32_e32 v179, v108, v109
	v_add_f32_e32 v180, v110, v111
	v_add_f32_e32 v181, v112, v113
	v_add_f32_e32 v178, v178, v179
	v_add_f32_e32 v180, v180, v181
	v_add_f32_e32 v178, v178, v180
	v_add_f32_e32 v210, v210, v178
	s_cmp_gt_u32 s35, 33
	s_cbranch_scc1 .Latt_nd3
	v_add_co_u32_e32 v130, vcc, v142, v130
	s_nop 1
	v_addc_co_u32_e32 v131, vcc, 0, v131, vcc
	v_add_co_u32_e32 v132, vcc, v143, v132
	s_nop 1
	v_addc_co_u32_e32 v133, vcc, 0, v133, vcc
	v_add_co_u32_e32 v134, vcc, v144, v134
	s_nop 1
	v_addc_co_u32_e32 v135, vcc, 0, v135, vcc
	v_add_co_u32_e32 v136, vcc, v145, v136
	s_nop 1
	v_addc_co_u32_e32 v137, vcc, 0, v137, vcc
	v_add_co_u32_e32 v138, vcc, 0x40000, v138
	s_nop 1
	v_addc_co_u32_e32 v139, vcc, 0, v139, vcc
	v_add_co_u32_e32 v140, vcc, 0x40000, v140
	s_nop 1
	v_addc_co_u32_e32 v141, vcc, 0, v141, vcc
.Latt_nd3:
	ds_read_b64_tr_b16 v[106:107], v184 offset:56320
	ds_read_b64_tr_b16 v[108:109], v184 offset:56832
	ds_read_b64_tr_b16 v[110:111], v184 offset:60416
	s_waitcnt lgkmcnt(11)
	ds_read_b64_tr_b16 v[112:113], v184 offset:60928
	v_exp_f32_e32 v2, v2
	v_exp_f32_e32 v3, v3
	v_exp_f32_e32 v4, v4
	v_mfma_f32_32x32x16_bf16 v[34:49], v[78:81], v[240:243], v[34:49]
	v_exp_f32_e32 v5, v5
	v_exp_f32_e32 v6, v6
	v_exp_f32_e32 v7, v7
	v_exp_f32_e32 v8, v8
	v_exp_f32_e32 v9, v9
	v_cvt_pk_bf16_f32 v66, v2, v3
	v_cvt_pk_bf16_f32 v67, v4, v5
	v_mfma_f32_32x32x16_bf16 v[50:65], v[78:81], v[244:247], v[50:65]
	v_cvt_pk_bf16_f32 v68, v6, v7
	v_cvt_pk_bf16_f32 v69, v8, v9
	v_add_f32_e32 v178, v2, v3
	v_add_f32_e32 v179, v4, v5
	v_add_f32_e32 v180, v6, v7
	v_add_f32_e32 v181, v8, v9
	v_add_f32_e32 v178, v178, v179
	v_add_f32_e32 v180, v180, v181
	v_add_f32_e32 v178, v178, v180
	v_add_f32_e32 v210, v210, v178
	v_exp_f32_e32 v10, v10
	v_exp_f32_e32 v11, v11
	v_exp_f32_e32 v12, v12
	v_mfma_f32_32x32x16_bf16 v[34:49], v[66:69], v[114:117], v[34:49]
	v_exp_f32_e32 v13, v13
	v_exp_f32_e32 v14, v14
	v_exp_f32_e32 v15, v15
	v_exp_f32_e32 v16, v16
	v_exp_f32_e32 v17, v17
	v_cvt_pk_bf16_f32 v70, v10, v11
	v_cvt_pk_bf16_f32 v71, v12, v13
	v_mfma_f32_32x32x16_bf16 v[50:65], v[66:69], v[118:121], v[50:65]
	v_cvt_pk_bf16_f32 v72, v14, v15
	v_cvt_pk_bf16_f32 v73, v16, v17
	v_add_f32_e32 v178, v10, v11
	v_add_f32_e32 v179, v12, v13
	v_add_f32_e32 v180, v14, v15
	v_add_f32_e32 v181, v16, v17
	v_add_f32_e32 v178, v178, v179
	v_add_f32_e32 v180, v180, v181
	v_add_f32_e32 v178, v178, v180
	v_add_f32_e32 v210, v210, v178
	v_exp_f32_e32 v18, v18
	v_exp_f32_e32 v19, v19
	v_exp_f32_e32 v20, v20
	s_waitcnt lgkmcnt(10)
	v_mfma_f32_32x32x16_bf16 v[34:49], v[70:73], v[122:125], v[34:49]
	v_exp_f32_e32 v21, v21
	v_exp_f32_e32 v22, v22
	v_exp_f32_e32 v23, v23
	v_exp_f32_e32 v24, v24
	v_exp_f32_e32 v25, v25
	v_cvt_pk_bf16_f32 v74, v18, v19
	v_cvt_pk_bf16_f32 v75, v20, v21
	s_waitcnt lgkmcnt(8)
	v_mfma_f32_32x32x16_bf16 v[50:65], v[70:73], v[126:129], v[50:65]
	v_cvt_pk_bf16_f32 v76, v22, v23
	v_cvt_pk_bf16_f32 v77, v24, v25
	v_add_f32_e32 v178, v18, v19
	v_add_f32_e32 v179, v20, v21
	v_add_f32_e32 v180, v22, v23
	v_add_f32_e32 v181, v24, v25
	v_add_f32_e32 v178, v178, v179
	v_add_f32_e32 v180, v180, v181
	v_add_f32_e32 v178, v178, v180
	v_add_f32_e32 v210, v210, v178
	v_exp_f32_e32 v26, v26
	v_exp_f32_e32 v27, v27
	v_exp_f32_e32 v28, v28
	s_waitcnt lgkmcnt(6)
	v_mfma_f32_32x32x16_bf16 v[34:49], v[74:77], v[98:101], v[34:49]
	v_exp_f32_e32 v29, v29
	v_exp_f32_e32 v30, v30
	v_exp_f32_e32 v31, v31
	v_exp_f32_e32 v32, v32
	v_exp_f32_e32 v33, v33
	v_cvt_pk_bf16_f32 v78, v26, v27
	v_cvt_pk_bf16_f32 v79, v28, v29
	s_waitcnt lgkmcnt(4)
	v_mfma_f32_32x32x16_bf16 v[50:65], v[74:77], v[102:105], v[50:65]
	v_cvt_pk_bf16_f32 v80, v30, v31
	v_cvt_pk_bf16_f32 v81, v32, v33
	v_add_f32_e32 v178, v26, v27
	v_add_f32_e32 v179, v28, v29
	v_add_f32_e32 v180, v30, v31
	v_add_f32_e32 v181, v32, v33
	v_add_f32_e32 v178, v178, v179
	v_add_f32_e32 v180, v180, v181
	v_add_f32_e32 v178, v178, v180
	v_add_f32_e32 v210, v210, v178
	s_waitcnt lgkmcnt(2)
	v_mfma_f32_32x32x16_bf16 v[34:49], v[78:81], v[106:109], v[34:49]
	s_waitcnt lgkmcnt(0)
	v_mfma_f32_32x32x16_bf16 v[50:65], v[78:81], v[110:113], v[50:65]
	s_cmp_eq_u32 s35, 0
	s_cbranch_scc1 .Latt_rs
	v_cmp_lt_f32_e32 vcc, 0x4b800000, v210
	s_cbranch_vccnz .Latt_rs
